# attention: V^T LDS tile stored key-permuted (pitch 144 B) so each PV fragment is one ds_read_b128 instead of ds_read2_b64 (half-rate); on top of v14
# baseline (speedup 1.0000x reference)
; DI void attn_phase(PPtr p, int j, ldsp lds, int tid, int wave, int lane) {
;     ...
;     constexpr int KP = 104, VP = 68, KBYTES = 64 * KP * 2, VBYTES = 64 * VP * 2, BUF = KBYTES + VBYTES;
;     const int r = lane & 31, hi = lane >> 5;
;     const int k1row = tid / 12, k1ch = tid % 12, k2row = (tid + 512) / 12, k2ch = (tid + 512) % 12, vrow = tid >> 3, vch = tid & 7;
;     float mfix;
;     { float gq = fabsf(p->mla_q_gain[j * QKH + lane]), gk = fabsf(p->mla_k_gain[j * QKH + lane]);
;       if (lane < 32) { gq = fmaxf(gq, fabsf(p->mla_q_gain[j * QKH + 64 + lane])); gk = fmaxf(gk, fabsf(p->mla_k_gain[j * QKH + 64 + lane])); }
; #pragma unroll
;       for (int o = 1; o < 64; o <<= 1) { gq = fmaxf(gq, __shfl_xor(gq, o)); gk = fmaxf(gk, __shfl_xor(gk, o)); }
;       mfix = QSCALE * 96.0f * gq * gk; }
.LBB0_845:
	s_or_b64 exec, exec, s[4:5]
	v_xor_b32_e32 v2, 1, v204
	v_cmp_lt_i32_e32 vcc, v2, v214
	v_max_f32_e32 v4, v10, v10
	s_nop 0
	v_cndmask_b32_e32 v2, v204, v2, vcc
	v_lshlrev_b32_e32 v2, 2, v2
	ds_bpermute_b32 v3, v2, v10
	ds_bpermute_b32 v2, v2, v0
	v_max_f32_e32 v0, v0, v0
	s_waitcnt lgkmcnt(1)
	v_max_f32_e32 v3, v3, v3
	s_waitcnt lgkmcnt(0)
	v_max_f32_e32 v2, v2, v2
	v_max_f32_e32 v0, v0, v2
	v_xor_b32_e32 v2, 2, v204
	v_cmp_lt_i32_e32 vcc, v2, v214
	v_max_f32_e32 v3, v4, v3
	s_nop 0
	v_cndmask_b32_e32 v2, v204, v2, vcc
	v_lshlrev_b32_e32 v2, 2, v2
	ds_bpermute_b32 v4, v2, v3
	ds_bpermute_b32 v2, v2, v0
	s_waitcnt lgkmcnt(1)
	v_max_f32_e32 v4, v4, v4
	s_waitcnt lgkmcnt(0)
	v_max_f32_e32 v2, v2, v2
	v_max_f32_e32 v0, v0, v2
	v_xor_b32_e32 v2, 4, v204
	v_cmp_lt_i32_e32 vcc, v2, v214
	v_max_f32_e32 v3, v3, v4
	s_nop 0
	v_cndmask_b32_e32 v2, v204, v2, vcc
	v_lshlrev_b32_e32 v2, 2, v2
	ds_bpermute_b32 v4, v2, v3
	ds_bpermute_b32 v2, v2, v0
	s_waitcnt lgkmcnt(1)
	v_max_f32_e32 v4, v4, v4
	s_waitcnt lgkmcnt(0)
	v_max_f32_e32 v2, v2, v2
	v_max_f32_e32 v0, v0, v2
	v_xor_b32_e32 v2, 8, v204
	v_cmp_lt_i32_e32 vcc, v2, v214
	v_max_f32_e32 v3, v3, v4
	s_nop 0
	v_cndmask_b32_e32 v2, v204, v2, vcc
	v_lshlrev_b32_e32 v2, 2, v2
	ds_bpermute_b32 v4, v2, v3
	ds_bpermute_b32 v2, v2, v0
	s_waitcnt lgkmcnt(1)
	v_max_f32_e32 v4, v4, v4
	s_waitcnt lgkmcnt(0)
	v_max_f32_e32 v2, v2, v2
	v_max_f32_e32 v2, v0, v2
	v_xor_b32_e32 v0, 16, v204
	v_cmp_lt_i32_e32 vcc, v0, v214
	v_max_f32_e32 v3, v3, v4
	s_nop 0
	v_cndmask_b32_e32 v0, v204, v0, vcc
	v_lshlrev_b32_e32 v4, 2, v0
	ds_bpermute_b32 v0, v4, v3
	s_waitcnt lgkmcnt(0)
	v_max_f32_e32 v0, v0, v0
	v_max_f32_e32 v0, v3, v0
	ds_bpermute_b32 v3, v4, v2
	s_waitcnt lgkmcnt(0)
	v_max_f32_e32 v3, v3, v3
	v_max_f32_e32 v2, v2, v3
	v_xor_b32_e32 v3, 32, v204
	v_cmp_lt_i32_e32 vcc, v3, v214
	s_nop 1
	v_cndmask_b32_e32 v3, v204, v3, vcc
	v_lshlrev_b32_e32 v155, 2, v3
	ds_bpermute_b32 v3, v155, v0
	ds_bpermute_b32 v4, v155, v2
	s_and_b64 vcc, exec, s[0:1]
	s_cbranch_vccnz .LBB0_870
	s_mov_b32 s0, 0x2aaaaaab
	v_mul_hi_i32 v5, v6, s0
	v_lshrrev_b32_e32 v8, 31, v5
	v_ashrrev_i32_e32 v5, 1, v5
	v_add_u32_e32 v10, v5, v8
	v_add_u32_e32 v8, 0x200, v6
	v_mul_hi_i32 v9, v8, s0
	v_lshrrev_b32_e32 v11, 31, v9
	v_ashrrev_i32_e32 v9, 1, v9
	s_waitcnt lgkmcnt(0)
	v_max_f32_e32 v4, v4, v4
	v_max_f32_e32 v2, v2, v2
	v_add_u32_e32 v11, v9, v11
	v_max_f32_e32 v13, v2, v4
	v_max_f32_e32 v2, v3, v3
	v_max_f32_e32 v0, v0, v0
	v_lshrrev_b32_e32 v7, 5, v7
	v_mul_lo_u32 v9, v11, 12
	v_max_f32_e32 v0, v0, v2
	v_sub_u32_e32 v12, v8, v9
	v_ashrrev_i32_e32 v8, 3, v6
	v_mul_f32_e32 v14, 0xc1622ae0, v0
	v_lshlrev_b32_e32 v0, 4, v7
	v_lshl_add_u64 v[2:3], s[2:3], 0, v[0:1]
	s_mov_b64 s[0:1], 0x15a40000
	v_ashrrev_i32_e32 v9, 31, v8
	s_movk_i32 s4, 0x68
	v_mul_lo_u32 v5, v10, 12
	v_lshl_add_u64 v[158:159], v[2:3], 0, s[0:1]
	v_lshlrev_b64 v[2:3], 13, v[8:9]
	v_lshlrev_b32_e32 v0, 3, v6
	v_mul_lo_u32 v9, v10, s4
	s_movk_i32 s4, 0x90
	v_and_b32_e32 v218, 31, v6
	v_sub_u32_e32 v5, v6, v5
	v_and_b32_e32 v0, 56, v0
	v_mul_lo_u32 v8, v8, s4
	v_lshlrev_b32_e32 v156, 3, v7
	v_mov_b32_e32 v157, v1
	v_lshlrev_b32_e32 v162, 3, v5
	v_and_b32_e32 v236, 0x30, v0
	v_lshl_add_u32 v220, v236, 1, v8
	v_and_b32_e32 v236, 8, v0
	v_add_u32_e32 v220, v220, v236
	v_mul_u32_u24_e32 v8, 0x68, v218
	s_movk_i32 s4, 0xd0
	s_add_u32 s8, s2, 0x18a40000
	s_movk_i32 s11, 0xc00
	v_add_lshl_u32 v219, v9, v162, 1
	v_add_lshl_u32 v221, v156, v8, 1
	v_mul_lo_u32 v225, v11, s4
	v_lshl_add_u64 v[8:9], s[2:3], 0, v[156:157]
	s_mov_b64 s[4:5], 0x1da40000
	s_addc_u32 s9, s3, 0
	s_ashr_i32 s10, s6, 1
	v_lshl_add_u64 v[4:5], s[2:3], 0, v[2:3]
	v_lshl_add_u64 v[166:167], v[8:9], 0, s[4:5]
	v_mad_i64_i32 v[168:169], s[4:5], v11, s11, 0
	v_lshlrev_b32_e32 v0, 1, v0
	s_andn2_b32 s10, s10, 31
	v_lshl_add_u64 v[4:5], v[4:5], 0, v[0:1]
	s_mov_b64 s[4:5], 0x1ba40000
	v_and_b32_e32 v0, 7, v6
	v_lshlrev_b32_e32 v164, 3, v12
	v_lshl_add_u64 v[170:171], v[4:5], 0, s[4:5]
	s_add_u32 s4, s2, 0x18a70000
	v_lshl_or_b32 v2, v0, 4, v2
	v_ashrrev_i32_e32 v163, 31, v162
	v_ashrrev_i32_e32 v165, 31, v164
	s_addc_u32 s5, s3, 0
	v_lshl_add_u64 v[2:3], s[2:3], 0, v[2:3]
	s_mov_b64 s[2:3], 0x1ba40080
	v_mad_i64_i32 v[160:161], s[0:1], v10, s11, 0
	v_lshlrev_b32_e32 v224, 4, v12
	v_lshlrev_b64 v[4:5], 1, v[164:165]
	v_lshl_add_u64 v[174:175], v[2:3], 0, s[2:3]
	v_lshlrev_b64 v[2:3], 1, v[162:163]
	s_movk_i32 s0, 0x100
	v_mul_f32_e32 v16, v14, v13
	v_lshlrev_b32_e32 v223, 2, v7
	v_add_u32_e32 v7, 0, v224
	v_mad_i64_i32 v[4:5], s[6:7], v11, s11, v[4:5]
	v_mad_i64_i32 v[2:3], s[2:3], v10, s11, v[2:3]
	v_cmp_gt_i32_e64 s[0:1], s0, v6
	v_mul_u32_u24_e32 v222, 0x90, v218
	v_add_u32_e32 v222, v222, v156
	v_mov_b32_e32 v17, v16
	v_mov_b32_e32 v18, v16
	v_mov_b32_e32 v19, v16
	v_mov_b32_e32 v20, v16
	v_mov_b32_e32 v21, v16
	v_mov_b32_e32 v22, v16
	v_mov_b32_e32 v23, v16
	v_mov_b32_e32 v24, v16
	v_mov_b32_e32 v25, v16
	v_mov_b32_e32 v26, v16
	v_mov_b32_e32 v27, v16
	v_mov_b32_e32 v28, v16
	v_mov_b32_e32 v29, v16
	v_mov_b32_e32 v30, v16
	v_mov_b32_e32 v31, v16
	v_lshl_add_u64 v[172:173], s[4:5], 0, v[4:5]
	v_lshl_add_u64 v[176:177], s[4:5], 0, v[2:3]
	v_add_u32_e32 v157, v7, v225
	s_mov_b32 s11, s64
	s_branch .LBB0_848

; #define ATT_LOAD(kt) do { kr1 = *(const u32x4*)(kbase + (size_t)(64 * (kt) + k1row) * (HEADS * QKH) + k1ch * 8); \
;                 if (tid < 256) kr2 = *(const u32x4*)(kbase + (size_t)(64 * (kt) + k2row) * (HEADS * QKH) + k2ch * 8); \
;                 vr = *(const u32x4*)(vbase + (size_t)vrow * SEQ + 64 * (kt) + vch * 8); } while (0)
; DI void attn_phase(PPtr p, int j, ldsp lds, int tid, int wave, int lane) {
;     ...
;             f32x16 o0, o1;
; #pragma unroll
;             for (int i = 0; i < 16; ++i) { o0[i] = 0.f; o1[i] = 0.f; }
;             float lrun = 0.f;
;             u32x4 kr1, kr2 = {0u, 0u, 0u, 0u}, vr;
;     ...
;             ATT_LOAD(0); ATT_STORE(0);
;             __syncthreads();
.LBB0_852:
	s_or_b64 exec, exec, s[2:3]
	global_load_dwordx4 v[128:131], v[180:181], off
	v_add_u32_e32 v0, 0, v219
	s_waitcnt vmcnt(1)
	ds_write_b128 v0, v[120:123]
	s_and_saveexec_b64 s[2:3], s[0:1]
	ds_write_b128 v157, v[124:127]
	s_or_b64 exec, exec, s[2:3]
	v_add_u32_e32 v0, 0, v220
	v_add_u32_e32 v0, 0x3400, v0
	v_mov_b32_e32 v14, v1
	v_mov_b32_e32 v15, v1
	s_lshl_b32 s17, s6, 2
	s_waitcnt vmcnt(0)
	ds_write2_b64 v0, v[128:129], v[130:131] offset1:2
	v_mov_b32_e32 v0, v1
	v_mov_b32_e32 v2, v1
	v_mov_b32_e32 v3, v1
	v_mov_b32_e32 v4, v1
	v_mov_b32_e32 v5, v1
	v_mov_b32_e32 v6, v1
	v_mov_b32_e32 v7, v1
	v_mov_b32_e32 v8, v1
	v_mov_b32_e32 v9, v1
	v_mov_b32_e32 v10, v1
	v_mov_b32_e32 v11, v1
	v_mov_b32_e32 v12, v1
	v_mov_b32_e32 v13, v1
	v_mov_b64_e32 v[62:63], v[14:15]
	v_mov_b64_e32 v[46:47], v[14:15]
	s_xor_b64 s[2:3], s[4:5], -1
	s_add_i32 s17, s17, 4
	s_or_b32 s18, s16, 31
	s_addk_i32 s19, 0x100
	s_mov_b32 s20, 0
	v_mov_b32_e32 v227, 0
	s_mov_b32 s21, 1
	v_mov_b64_e32 v[194:195], v[190:191]
	v_mov_b64_e32 v[196:197], v[188:189]
	v_mov_b64_e32 v[198:199], v[186:187]
	v_mov_b64_e32 v[60:61], v[12:13]
	v_mov_b64_e32 v[58:59], v[10:11]
	v_mov_b64_e32 v[56:57], v[8:9]
	v_mov_b64_e32 v[54:55], v[6:7]
	v_mov_b64_e32 v[52:53], v[4:5]
	v_mov_b64_e32 v[50:51], v[2:3]
	v_mov_b64_e32 v[48:49], v[0:1]
	v_mov_b64_e32 v[44:45], v[12:13]
	v_mov_b64_e32 v[42:43], v[10:11]
	v_mov_b64_e32 v[40:41], v[8:9]
	v_mov_b64_e32 v[38:39], v[6:7]
	v_mov_b64_e32 v[36:37], v[4:5]
	v_mov_b64_e32 v[34:35], v[2:3]
	v_mov_b64_e32 v[32:33], v[0:1]
	s_waitcnt lgkmcnt(0)
	s_barrier
	s_branch .LBB0_857
.LBB0_855:
	s_or_b64 exec, exec, s[4:5]
	v_add_u32_e32 v0, s6, v220
	v_add_u32_e32 v0, 0x3400, v0
	s_waitcnt vmcnt(0)
	ds_write2_b64 v0, v[128:129], v[130:131] offset1:2

; #define LAS __attribute__((address_space(3)))
; #define MFMA32(a, b, c) __builtin_amdgcn_mfma_f32_32x32x16_bf16((a), (b), (c), 0, 0, 0)
; DI void attn_phase(PPtr p, int j, ldsp lds, int tid, int wave, int lane) {
;     ...
;                     const ldsp kb0 = lds + buf * BUF + (r * KP + 8 * hi) * 2;
;                     bf16x8 ka[6], kc[6];
; #pragma unroll
;                     for (int ks = 0; ks < 6; ++ks) { ka[ks] = *(const LAS bf16x8*)(kb0 + ks * 32); kc[ks] = *(const LAS bf16x8*)(kb0 + 32 * KP * 2 + ks * 32); }
;                     __builtin_amdgcn_sched_barrier(0);
; #pragma unroll
;                     for (int ks = 0; ks < 6; ++ks) s0 = MFMA32(ka[ks], qf[ks], s0);
; #pragma unroll
;                     for (int ks = 0; ks < 6; ++ks) s1 = MFMA32(kc[ks], qf[ks], s1);
;                     const ldsp vb0 = lds + buf * BUF + KBYTES + (r * VP + 4 * hi) * 2;
;                     s16x4 vlo0[4], vhi0[4], vlo1[4], vhi1[4];
; #pragma unroll
;                     for (int q = 0; q < 4; ++q) { const ldsp va = vb0 + (16 * q) * 2;
;                         vlo0[q] = *(const LAS s16x4*)(va); vhi0[q] = *(const LAS s16x4*)(va + 16);
;                         vlo1[q] = *(const LAS s16x4*)(va + 32 * VP * 2); vhi1[q] = *(const LAS s16x4*)(va + 32 * VP * 2 + 16); }
.LBB0_863:
	s_mul_i32 s6, s22, 0x5800
	s_add_i32 s6, s6, 0
	v_add_u32_e32 v0, s6, v221
	ds_read_b128 v[2:5], v0
	ds_read_b128 v[6:9], v0 offset:32
	ds_read_b128 v[10:13], v0 offset:6656
	ds_read_b128 v[132:135], v0 offset:6688
	ds_read_b128 v[64:67], v0 offset:64
	ds_read_b128 v[68:71], v0 offset:96
	ds_read_b128 v[136:139], v0 offset:6720
	ds_read_b128 v[140:143], v0 offset:6752
	ds_read_b128 v[72:75], v0 offset:128
	ds_read_b128 v[228:231], v0 offset:160
	ds_read_b128 v[144:147], v0 offset:6784
	ds_read_b128 v[232:235], v0 offset:6816
	s_waitcnt lgkmcnt(11)
	v_mfma_f32_32x32x16_bf16 v[80:95], v[2:5], v[116:119], v[16:31]
	v_add3_u32 v0, s6, v156, v222
	v_add_u32_e32 v2, 0x3000, v0
	v_add_u32_e32 v0, 0x4000, v0
	s_add_i32 s23, s20, 63
	s_cmp_gt_i32 s23, s16
	s_cselect_b64 s[6:7], -1, 0
	s_cmp_le_i32 s23, s16
	s_waitcnt lgkmcnt(10)
	v_mfma_f32_32x32x16_bf16 v[80:95], v[6:9], v[96:99], v[80:95]
	s_waitcnt lgkmcnt(7)
	v_mfma_f32_32x32x16_bf16 v[80:95], v[64:67], v[100:103], v[80:95]
	s_waitcnt lgkmcnt(6)
	v_mfma_f32_32x32x16_bf16 v[80:95], v[68:71], v[104:107], v[80:95]
	s_waitcnt lgkmcnt(3)
	v_mfma_f32_32x32x16_bf16 v[80:95], v[72:75], v[108:111], v[80:95]
	v_mfma_f32_32x32x16_bf16 v[64:79], v[10:13], v[116:119], v[16:31]
	v_mfma_f32_32x32x16_bf16 v[64:79], v[132:135], v[96:99], v[64:79]
	v_mfma_f32_32x32x16_bf16 v[64:79], v[136:139], v[100:103], v[64:79]
	ds_read_b128 v[148:151], v2 offset:1024
	ds_read_b128 v[136:139], v2 offset:1056
	v_mfma_f32_32x32x16_bf16 v[64:79], v[140:143], v[104:107], v[64:79]
	s_waitcnt lgkmcnt(3)
	v_mfma_f32_32x32x16_bf16 v[64:79], v[144:147], v[108:111], v[64:79]
	ds_read_b128 v[144:147], v0 offset:1536
	ds_read_b128 v[140:143], v0 offset:1568
	ds_read_b128 v[132:135], v2 offset:1088
	ds_read_b128 v[10:13], v0 offset:1600
	ds_read_b128 v[6:9], v2 offset:1120
	ds_read_b128 v[2:5], v0 offset:1632
	v_add_u32_e32 v0, s20, v223
	s_waitcnt lgkmcnt(8)
	v_mfma_f32_32x32x16_bf16 v[64:79], v[232:235], v[112:115], v[64:79]
	v_mfma_f32_32x32x16_bf16 v[80:95], v[228:231], v[112:115], v[80:95]
	s_cbranch_scc1 .LBB0_865
	v_cmp_lt_i32_e32 vcc, v0, v226
	v_add_u32_e32 v14, 2, v0
	s_nop 8
	v_cndmask_b32_e32 v81, v217, v81, vcc
	v_cmp_le_i32_e32 vcc, v0, v226
	s_nop 1
	v_cndmask_b32_e32 v80, v217, v80, vcc
	v_cmp_le_i32_e32 vcc, v14, v226
	v_add_u32_e32 v14, 3, v0
	s_nop 0
	v_cndmask_b32_e32 v82, v217, v82, vcc
	v_cmp_le_i32_e32 vcc, v14, v226
	v_add_u32_e32 v14, 8, v0
	s_nop 0
	v_cndmask_b32_e32 v83, v217, v83, vcc
	v_cmp_le_i32_e32 vcc, v14, v226
	v_add_u32_e32 v14, 9, v0
	s_nop 0
	v_cndmask_b32_e32 v84, v217, v84, vcc
	v_cmp_le_i32_e32 vcc, v14, v226
	v_add_u32_e32 v14, 10, v0
	s_nop 0
	v_cndmask_b32_e32 v85, v217, v85, vcc
	v_cmp_le_i32_e32 vcc, v14, v226
	v_add_u32_e32 v14, 11, v0
	s_nop 0
	v_cndmask_b32_e32 v86, v217, v86, vcc
	v_cmp_le_i32_e32 vcc, v14, v226
	v_add_u32_e32 v14, 16, v0
	s_nop 0
	v_cndmask_b32_e32 v87, v217, v87, vcc
	v_cmp_le_i32_e32 vcc, v14, v226
	v_add_u32_e32 v14, 17, v0
	s_nop 0
	v_cndmask_b32_e32 v88, v217, v88, vcc
	v_cmp_le_i32_e32 vcc, v14, v226
	v_add_u32_e32 v14, 18, v0
	s_nop 0
	v_cndmask_b32_e32 v89, v217, v89, vcc
	v_cmp_le_i32_e32 vcc, v14, v226
	v_add_u32_e32 v14, 19, v0
	s_nop 0
	v_cndmask_b32_e32 v90, v217, v90, vcc
	v_cmp_le_i32_e32 vcc, v14, v226
	v_add_u32_e32 v14, 24, v0
	s_nop 0
	v_cndmask_b32_e32 v91, v217, v91, vcc
	v_cmp_le_i32_e32 vcc, v14, v226
	v_add_u32_e32 v14, 25, v0
	s_nop 0
	v_cndmask_b32_e32 v92, v217, v92, vcc
	v_cmp_le_i32_e32 vcc, v14, v226
	v_add_u32_e32 v14, 26, v0
	s_nop 0
	v_cndmask_b32_e32 v93, v217, v93, vcc
	v_cmp_le_i32_e32 vcc, v14, v226
	v_add_u32_e32 v14, 27, v0
	s_nop 0
	v_cndmask_b32_e32 v94, v217, v94, vcc
	v_cmp_le_i32_e32 vcc, v14, v226
	s_nop 1
	v_cndmask_b32_e32 v95, v217, v95, vcc

.LBB0_868:
	s_xor_b32 s4, s22, 1
	s_mulk_i32 s4, 0x5800
	s_add_i32 s6, s4, 0
	v_add_u32_e32 v0, s6, v219
	s_waitcnt vmcnt(1)
	ds_write_b128 v0, v[120:123]
	s_and_saveexec_b64 s[4:5], s[0:1]
	s_cbranch_execz .LBB0_855
	v_add3_u32 v0, s6, v224, v225
	ds_write_b128 v0, v[124:127]
	s_branch .LBB0_855
